# MLA loop: v_exp spread two per S^T MFMA gap instead of bunched in the first gaps
# baseline (speedup 1.0000x reference)
.LBB0_859:
	v_exp_f32_e32 v97, v97
	v_exp_f32_e32 v99, v99
	ds_read_b128 v[236:239], v214 offset:8192
	ds_read_b128 v[240:243], v215 offset:8192
	ds_read_b128 v[244:247], v216 offset:8192
	ds_read_b128 v[248:251], v217 offset:8192
	ds_read_b128 v[252:255], v218 offset:8192
	ds_read_b128 v[176:179], v219 offset:8192
	s_waitcnt lgkmcnt(4)
	v_mfma_f32_32x32x16_bf16 v[80:95], v[236:239], v[144:147], v[64:79]
	ds_read_b128 v[180:183], v220 offset:8192
	v_exp_f32_e32 v100, v100
	v_exp_f32_e32 v101, v101
	v_mfma_f32_32x32x16_bf16 v[80:95], v[240:243], v[156:159], v[80:95]
	ds_read_b128 v[236:239], v221 offset:8192
	v_exp_f32_e32 v102, v102
	v_exp_f32_e32 v103, v103
	s_add_u32 s98, s34, s60
	s_addc_u32 s99, s35, s59
	s_add_u32 s98, s98, 0x140fc000
	s_addc_u32 s99, s99, 0
	s_add_u32 s100, s34, s62
	s_addc_u32 s101, s35, s61
	s_add_u32 s100, s100, 0x171b0100
	s_addc_u32 s101, s101, 0
	s_mov_b32 m0, s52
	s_cmp_lg_u64 s[24:25], 0
	s_cselect_b32 s4, s100, s98
	s_cselect_b32 s5, s101, s99
	global_load_lds_dwordx4 v190, s[4:5]
	s_mov_b32 m0, s53
	s_cmp_lg_u64 s[26:27], 0
	s_cselect_b32 s4, s100, s98
	s_cselect_b32 s5, s101, s99
	global_load_lds_dwordx4 v192, s[4:5]
	s_mov_b32 m0, s54
	s_cmp_lg_u64 s[28:29], 0
	s_cselect_b32 s4, s100, s98
	s_cselect_b32 s5, s101, s99
	global_load_lds_dwordx4 v194, s[4:5]
	s_mov_b32 m0, s55
	s_cmp_lg_u64 s[30:31], 0
	s_cselect_b32 s4, s100, s98
	s_cselect_b32 s5, s101, s99
	global_load_lds_dwordx4 v196, s[4:5]
	s_mov_b32 m0, s56
	s_cmp_lg_u64 s[6:7], 0
	s_cselect_b32 s4, s100, s98
	s_cselect_b32 s5, s101, s99
	global_load_lds_dwordx4 v198, s[4:5]
	s_waitcnt lgkmcnt(4)
	v_mfma_f32_32x32x16_bf16 v[80:95], v[244:247], v[168:171], v[80:95]
	ds_read_b128 v[240:243], v205 offset:53248
	v_exp_f32_e32 v106, v106
	v_exp_f32_e32 v107, v107
	v_mfma_f32_32x32x16_bf16 v[80:95], v[248:251], v[172:175], v[80:95]
	ds_read_b128 v[244:247], v207 offset:53248
	v_exp_f32_e32 v108, v108
	v_exp_f32_e32 v109, v109
	s_waitcnt lgkmcnt(4)
	v_mfma_f32_32x32x16_bf16 v[80:95], v[252:255], v[164:167], v[80:95]
	ds_read_b128 v[248:251], v209 offset:53248
	v_exp_f32_e32 v110, v110
	v_exp_f32_e32 v111, v111
	v_mfma_f32_32x32x16_bf16 v[80:95], v[176:179], v[160:163], v[80:95]
	ds_read_b128 v[252:255], v211 offset:53248
	s_waitcnt lgkmcnt(4)
	v_mfma_f32_32x32x16_bf16 v[80:95], v[180:183], v[152:155], v[80:95]
	ds_read_b128 v[176:179], v225
	v_mfma_f32_32x32x16_bf16 v[80:95], v[236:239], v[148:151], v[80:95]
	ds_read_b128 v[180:183], v225 offset:4096
	s_waitcnt lgkmcnt(4)
	v_mfma_f32_32x32x16_bf16 v[80:95], v[240:243], v[140:143], v[80:95]
	ds_read_b128 v[236:239], v225 offset:8192
	v_mfma_f32_32x32x16_bf16 v[80:95], v[244:247], v[136:139], v[80:95]
	ds_read_b128 v[240:243], v225 offset:12288
	s_waitcnt lgkmcnt(4)
	v_mfma_f32_32x32x16_bf16 v[80:95], v[248:251], v[132:135], v[80:95]
	ds_read_b128 v[244:247], v226
	v_mfma_f32_32x32x16_bf16 v[80:95], v[252:255], v[128:131], v[80:95]
	ds_read_b128 v[248:251], v226 offset:4096
	v_exp_f32_e32 v112, v96
	v_exp_f32_e32 v113, v98
	v_exp_f32_e32 v114, v104
	v_exp_f32_e32 v115, v105
	v_add_f32_e32 v96, 0, v112
	v_add_f32_e32 v96, v97, v96
	v_add_f32_e32 v96, v113, v96
	v_add_f32_e32 v96, v99, v96
	v_add_f32_e32 v96, v100, v96
	v_add_f32_e32 v96, v101, v96
	v_add_f32_e32 v96, v102, v96
	v_add_f32_e32 v96, v103, v96
	v_cvt_pk_bf16_f32 v100, v100, v101
	v_cvt_pk_bf16_f32 v101, v102, v103
	v_cvt_pk_bf16_f32 v98, v112, v97
	v_cvt_pk_bf16_f32 v99, v113, v99
	v_max_f32_e32 v97, v81, v81
	v_add_f32_e32 v96, v114, v96
	s_waitcnt lgkmcnt(4)
	v_mfma_f32_32x32x16_bf16 v[48:63], v[176:179], v[98:101], v[48:63]
	ds_read_b128 v[252:255], v226 offset:8192
	v_add_f32_e32 v96, v115, v96
	v_add_f32_e32 v96, v106, v96
	v_add_f32_e32 v96, v107, v96
	v_add_f32_e32 v96, v108, v96
	v_add_f32_e32 v96, v109, v96
	v_add_f32_e32 v96, v110, v96
	v_mfma_f32_32x32x16_bf16 v[32:47], v[180:183], v[98:101], v[32:47]
	ds_read_b128 v[176:179], v226 offset:12288
	v_add_f32_e32 v96, v111, v96
	v_add_f32_e32 v112, v230, v96
	s_waitcnt lgkmcnt(4)
	v_mfma_f32_32x32x16_bf16 v[16:31], v[236:239], v[98:101], v[16:31]
	ds_read_b128 v[180:183], v214 offset:16384
	v_mfma_f32_32x32x16_bf16 v[0:15], v[240:243], v[98:101], v[0:15]
	ds_read_b128 v[236:239], v215 offset:16384
	v_cvt_pk_bf16_f32 v98, v114, v115
	v_cvt_pk_bf16_f32 v99, v106, v107
	v_cvt_pk_bf16_f32 v100, v108, v109
	v_cvt_pk_bf16_f32 v101, v110, v111
	s_nop 0
	s_waitcnt lgkmcnt(4)
	v_mfma_f32_32x32x16_bf16 v[48:63], v[244:247], v[98:101], v[48:63]
	ds_read_b128 v[240:243], v216 offset:16384
	v_mfma_f32_32x32x16_bf16 v[32:47], v[248:251], v[98:101], v[32:47]
	ds_read_b128 v[244:247], v217 offset:16384
	s_waitcnt lgkmcnt(4)
	v_mfma_f32_32x32x16_bf16 v[16:31], v[252:255], v[98:101], v[16:31]
	ds_read_b128 v[248:251], v218 offset:16384
	v_mfma_f32_32x32x16_bf16 v[0:15], v[176:179], v[98:101], v[0:15]
	ds_read_b128 v[252:255], v219 offset:16384
	v_max_f32_e32 v98, v80, v80
	v_max_f32_e32 v97, v98, v97
	v_max3_f32 v97, v97, v82, v83
	v_max3_f32 v97, v97, v84, v85
	v_max3_f32 v97, v97, v86, v87
	v_max3_f32 v97, v97, v88, v89
	v_max3_f32 v97, v97, v90, v91
	v_max3_f32 v97, v97, v92, v93
	v_max3_f32 v97, v97, v94, v95
	ds_bpermute_b32 v98, v229, v97
	s_waitcnt lgkmcnt(0)
	v_max_f32_e32 v96, v98, v98
	v_max_f32_e32 v96, v97, v96
	v_cmp_lt_f32_e32 vcc, 0, v96
	s_cbranch_vccz .LBB0_861
	v_max_f32_e32 v96, v96, v96
	v_max_f32_e32 v96, 0, v96
	v_exp_f32_e64 v98, -v96
	v_pk_add_f32 v[80:81], v[80:81], v[96:97] op_sel_hi:[1,0] neg_lo:[0,1] neg_hi:[0,1]
	v_pk_add_f32 v[82:83], v[82:83], v[96:97] op_sel_hi:[1,0] neg_lo:[0,1] neg_hi:[0,1]
	v_pk_add_f32 v[84:85], v[84:85], v[96:97] op_sel_hi:[1,0] neg_lo:[0,1] neg_hi:[0,1]
	v_mul_f32_e32 v112, v112, v98
	v_pk_add_f32 v[86:87], v[86:87], v[96:97] op_sel_hi:[1,0] neg_lo:[0,1] neg_hi:[0,1]
	v_pk_add_f32 v[88:89], v[88:89], v[96:97] op_sel_hi:[1,0] neg_lo:[0,1] neg_hi:[0,1]
	v_pk_add_f32 v[90:91], v[90:91], v[96:97] op_sel_hi:[1,0] neg_lo:[0,1] neg_hi:[0,1]
	v_pk_add_f32 v[92:93], v[92:93], v[96:97] op_sel_hi:[1,0] neg_lo:[0,1] neg_hi:[0,1]
	v_sub_f32_e32 v79, v79, v96
	v_sub_f32_e32 v78, v78, v96
	v_sub_f32_e32 v77, v77, v96
	v_sub_f32_e32 v76, v76, v96
	v_sub_f32_e32 v75, v75, v96
	v_sub_f32_e32 v74, v74, v96
	v_sub_f32_e32 v73, v73, v96
	v_sub_f32_e32 v72, v72, v96
	v_sub_f32_e32 v71, v71, v96
	v_sub_f32_e32 v70, v70, v96
	v_sub_f32_e32 v69, v69, v96
	v_sub_f32_e32 v68, v68, v96
	v_sub_f32_e32 v67, v67, v96
	v_sub_f32_e32 v66, v66, v96
	v_sub_f32_e32 v65, v65, v96
	v_sub_f32_e32 v64, v64, v96
	v_pk_add_f32 v[94:95], v[94:95], v[96:97] op_sel_hi:[1,0] neg_lo:[0,1] neg_hi:[0,1]
	v_pk_mul_f32 v[62:63], v[62:63], v[98:99] op_sel_hi:[1,0]
	v_pk_mul_f32 v[60:61], v[60:61], v[98:99] op_sel_hi:[1,0]
	v_pk_mul_f32 v[58:59], v[58:59], v[98:99] op_sel_hi:[1,0]
	v_pk_mul_f32 v[56:57], v[56:57], v[98:99] op_sel_hi:[1,0]
	v_pk_mul_f32 v[54:55], v[54:55], v[98:99] op_sel_hi:[1,0]
	v_pk_mul_f32 v[52:53], v[52:53], v[98:99] op_sel_hi:[1,0]
	v_pk_mul_f32 v[50:51], v[50:51], v[98:99] op_sel_hi:[1,0]
	v_pk_mul_f32 v[48:49], v[48:49], v[98:99] op_sel_hi:[1,0]
	v_pk_mul_f32 v[46:47], v[46:47], v[98:99] op_sel_hi:[1,0]
	v_pk_mul_f32 v[44:45], v[44:45], v[98:99] op_sel_hi:[1,0]
	v_pk_mul_f32 v[42:43], v[42:43], v[98:99] op_sel_hi:[1,0]
	v_pk_mul_f32 v[40:41], v[40:41], v[98:99] op_sel_hi:[1,0]
	v_pk_mul_f32 v[38:39], v[38:39], v[98:99] op_sel_hi:[1,0]
	v_pk_mul_f32 v[36:37], v[36:37], v[98:99] op_sel_hi:[1,0]
	v_pk_mul_f32 v[34:35], v[34:35], v[98:99] op_sel_hi:[1,0]
	v_pk_mul_f32 v[32:33], v[32:33], v[98:99] op_sel_hi:[1,0]
	v_pk_mul_f32 v[30:31], v[30:31], v[98:99] op_sel_hi:[1,0]
	v_pk_mul_f32 v[28:29], v[28:29], v[98:99] op_sel_hi:[1,0]
	v_pk_mul_f32 v[26:27], v[26:27], v[98:99] op_sel_hi:[1,0]
	v_pk_mul_f32 v[24:25], v[24:25], v[98:99] op_sel_hi:[1,0]
	v_pk_mul_f32 v[22:23], v[22:23], v[98:99] op_sel_hi:[1,0]
	v_pk_mul_f32 v[20:21], v[20:21], v[98:99] op_sel_hi:[1,0]
	v_pk_mul_f32 v[18:19], v[18:19], v[98:99] op_sel_hi:[1,0]
	v_pk_mul_f32 v[16:17], v[16:17], v[98:99] op_sel_hi:[1,0]
	v_pk_mul_f32 v[14:15], v[14:15], v[98:99] op_sel_hi:[1,0]
	v_pk_mul_f32 v[12:13], v[12:13], v[98:99] op_sel_hi:[1,0]
	v_pk_mul_f32 v[10:11], v[10:11], v[98:99] op_sel_hi:[1,0]
	v_pk_mul_f32 v[8:9], v[8:9], v[98:99] op_sel_hi:[1,0]
	v_pk_mul_f32 v[6:7], v[6:7], v[98:99] op_sel_hi:[1,0]
	v_pk_mul_f32 v[4:5], v[4:5], v[98:99] op_sel_hi:[1,0]
	v_pk_mul_f32 v[2:3], v[2:3], v[98:99] op_sel_hi:[1,0]
	v_pk_mul_f32 v[0:1], v[0:1], v[98:99] op_sel_hi:[1,0]
.LBB0_861:
	v_exp_f32_e32 v113, v80
	v_exp_f32_e32 v122, v81
	v_mfma_f32_32x32x16_bf16 v[96:111], v[180:183], v[144:147], v[64:79]
	ds_read_b128 v[176:179], v220 offset:16384
	v_exp_f32_e32 v123, v82
	v_exp_f32_e32 v124, v83
	v_mfma_f32_32x32x16_bf16 v[96:111], v[236:239], v[156:159], v[96:111]
	ds_read_b128 v[180:183], v221 offset:16384
	v_exp_f32_e32 v125, v84
	v_exp_f32_e32 v126, v85
	v_mfma_f32_32x32x16_bf16 v[96:111], v[240:243], v[168:171], v[96:111]
	ds_read_b128 v[236:239], v205 offset:57344
	v_exp_f32_e32 v127, v86
	v_exp_f32_e32 v230, v87
	v_mfma_f32_32x32x16_bf16 v[96:111], v[244:247], v[172:175], v[96:111]
	ds_read_b128 v[240:243], v207 offset:57344
	v_exp_f32_e32 v88, v88
	v_exp_f32_e32 v89, v89
	v_mfma_f32_32x32x16_bf16 v[96:111], v[248:251], v[164:167], v[96:111]
	ds_read_b128 v[244:247], v209 offset:57344
	v_exp_f32_e32 v90, v90
	v_exp_f32_e32 v91, v91
	v_mfma_f32_32x32x16_bf16 v[96:111], v[252:255], v[160:163], v[96:111]
	ds_read_b128 v[248:251], v211 offset:57344
	v_exp_f32_e32 v92, v92
	v_exp_f32_e32 v93, v93
	s_waitcnt lgkmcnt(4)
	v_mfma_f32_32x32x16_bf16 v[96:111], v[176:179], v[152:155], v[96:111]
	ds_read_b128 v[252:255], v227
	v_exp_f32_e32 v94, v94
	v_exp_f32_e32 v95, v95
	v_mfma_f32_32x32x16_bf16 v[96:111], v[180:183], v[148:151], v[96:111]
	ds_read_b128 v[176:179], v227 offset:4096
	s_waitcnt lgkmcnt(4)
	v_mfma_f32_32x32x16_bf16 v[96:111], v[236:239], v[140:143], v[96:111]
	ds_read_b128 v[180:183], v227 offset:8192
	v_mfma_f32_32x32x16_bf16 v[96:111], v[240:243], v[136:139], v[96:111]
	ds_read_b128 v[236:239], v227 offset:12288
	s_waitcnt lgkmcnt(4)
	v_mfma_f32_32x32x16_bf16 v[96:111], v[244:247], v[132:135], v[96:111]
	ds_read_b128 v[240:243], v228 offset:4096
	v_cvt_pk_bf16_f32 v114, v113, v122
	v_cvt_pk_bf16_f32 v115, v123, v124
	v_cvt_pk_bf16_f32 v116, v125, v126
	v_cvt_pk_bf16_f32 v117, v127, v230
	v_mfma_f32_32x32x16_bf16 v[96:111], v[248:251], v[128:131], v[96:111]
	ds_read_b128 v[244:247], v228
	v_add_f32_e32 v118, 0, v113
	v_add_f32_e32 v113, v122, v118
	v_add_f32_e32 v113, v123, v113
	s_waitcnt lgkmcnt(4)
	v_mfma_f32_32x32x16_bf16 v[48:63], v[252:255], v[114:117], v[48:63]
	ds_read_b128 v[248:251], v228 offset:8192
	v_add_f32_e32 v80, v124, v113
	v_add_f32_e32 v80, v125, v80
	v_add_f32_e32 v80, v126, v80
	v_add_f32_e32 v113, v127, v80
	v_mfma_f32_32x32x16_bf16 v[32:47], v[176:179], v[114:117], v[32:47]
	ds_read_b128 v[252:255], v228 offset:12288
	v_add_f32_e32 v84, v230, v113
	v_add_f32_e32 v84, v88, v84
	v_add_f32_e32 v113, v89, v84
	s_waitcnt lgkmcnt(4)
	v_mfma_f32_32x32x16_bf16 v[16:31], v[180:183], v[114:117], v[16:31]
	ds_read_b128 v[176:179], v214 offset:24576
	v_add_f32_e32 v80, v90, v113
	v_add_f32_e32 v80, v91, v80
	v_add_f32_e32 v80, v92, v80
	v_add_f32_e32 v113, v93, v80
	v_add_f32_e32 v113, v94, v113
	v_mfma_f32_32x32x16_bf16 v[0:15], v[236:239], v[114:117], v[0:15]
	ds_read_b128 v[180:183], v215 offset:24576
	v_cvt_pk_bf16_f32 v84, v88, v89
	v_cvt_pk_bf16_f32 v85, v90, v91
	v_cvt_pk_bf16_f32 v86, v92, v93
	v_max_f32_e32 v92, v97, v97
	v_max_f32_e32 v93, v96, v96
	v_max_f32_e32 v92, v93, v92
	v_max3_f32 v92, v92, v98, v99
	v_max3_f32 v92, v92, v100, v101
	v_cvt_pk_bf16_f32 v87, v94, v95
	v_max3_f32 v92, v92, v102, v103
	v_add_f32_e32 v94, v95, v113
	s_waitcnt lgkmcnt(4)
	v_mfma_f32_32x32x16_bf16 v[32:47], v[240:243], v[84:87], v[32:47]
	ds_read_b128 v[236:239], v216 offset:24576
	v_max3_f32 v88, v92, v104, v105
	v_max3_f32 v88, v88, v106, v107
	v_max3_f32 v88, v88, v108, v109
	v_max3_f32 v92, v88, v110, v111
	ds_bpermute_b32 v93, v229, v92
	v_add_f32_e32 v112, v112, v94
	v_mfma_f32_32x32x16_bf16 v[48:63], v[244:247], v[84:87], v[48:63]
	ds_read_b128 v[240:243], v217 offset:24576
	s_waitcnt vmcnt(0)
	s_barrier
	s_waitcnt lgkmcnt(5)
	v_mfma_f32_32x32x16_bf16 v[16:31], v[248:251], v[84:87], v[16:31]
	ds_read_b128 v[244:247], v218 offset:24576
	s_waitcnt lgkmcnt(2)
	v_max_f32_e32 v80, v93, v93
	v_max_f32_e32 v80, v92, v80
	v_cmp_lt_f32_e32 vcc, 0, v80
	v_mfma_f32_32x32x16_bf16 v[0:15], v[252:255], v[84:87], v[0:15]
	ds_read_b128 v[248:251], v219 offset:24576
	s_cbranch_vccz .LBB0_863
	v_max_f32_e32 v80, v80, v80
	v_max_f32_e32 v80, 0, v80
	v_exp_f32_e64 v82, -v80
	v_pk_add_f32 v[96:97], v[96:97], v[80:81] op_sel_hi:[1,0] neg_lo:[0,1] neg_hi:[0,1]
	v_pk_add_f32 v[98:99], v[98:99], v[80:81] op_sel_hi:[1,0] neg_lo:[0,1] neg_hi:[0,1]
	v_pk_add_f32 v[100:101], v[100:101], v[80:81] op_sel_hi:[1,0] neg_lo:[0,1] neg_hi:[0,1]
	v_mul_f32_e32 v112, v112, v82
	v_pk_add_f32 v[102:103], v[102:103], v[80:81] op_sel_hi:[1,0] neg_lo:[0,1] neg_hi:[0,1]
	v_pk_add_f32 v[104:105], v[104:105], v[80:81] op_sel_hi:[1,0] neg_lo:[0,1] neg_hi:[0,1]
	v_pk_add_f32 v[106:107], v[106:107], v[80:81] op_sel_hi:[1,0] neg_lo:[0,1] neg_hi:[0,1]
	v_pk_add_f32 v[108:109], v[108:109], v[80:81] op_sel_hi:[1,0] neg_lo:[0,1] neg_hi:[0,1]
	v_sub_f32_e32 v79, v79, v80
	v_sub_f32_e32 v78, v78, v80
	v_sub_f32_e32 v77, v77, v80
	v_sub_f32_e32 v76, v76, v80
	v_sub_f32_e32 v75, v75, v80
	v_sub_f32_e32 v74, v74, v80
	v_sub_f32_e32 v73, v73, v80
	v_sub_f32_e32 v72, v72, v80
	v_sub_f32_e32 v71, v71, v80
	v_sub_f32_e32 v70, v70, v80
	v_sub_f32_e32 v69, v69, v80
	v_sub_f32_e32 v68, v68, v80
	v_sub_f32_e32 v67, v67, v80
	v_sub_f32_e32 v66, v66, v80
	v_sub_f32_e32 v65, v65, v80
	v_sub_f32_e32 v64, v64, v80
	v_pk_add_f32 v[110:111], v[110:111], v[80:81] op_sel_hi:[1,0] neg_lo:[0,1] neg_hi:[0,1]
	v_pk_mul_f32 v[62:63], v[62:63], v[82:83] op_sel_hi:[1,0]
	v_pk_mul_f32 v[60:61], v[60:61], v[82:83] op_sel_hi:[1,0]
	v_pk_mul_f32 v[58:59], v[58:59], v[82:83] op_sel_hi:[1,0]
	v_pk_mul_f32 v[56:57], v[56:57], v[82:83] op_sel_hi:[1,0]
	v_pk_mul_f32 v[54:55], v[54:55], v[82:83] op_sel_hi:[1,0]
	v_pk_mul_f32 v[52:53], v[52:53], v[82:83] op_sel_hi:[1,0]
	v_pk_mul_f32 v[50:51], v[50:51], v[82:83] op_sel_hi:[1,0]
	v_pk_mul_f32 v[48:49], v[48:49], v[82:83] op_sel_hi:[1,0]
	v_pk_mul_f32 v[46:47], v[46:47], v[82:83] op_sel_hi:[1,0]
	v_pk_mul_f32 v[44:45], v[44:45], v[82:83] op_sel_hi:[1,0]
	v_pk_mul_f32 v[42:43], v[42:43], v[82:83] op_sel_hi:[1,0]
	v_pk_mul_f32 v[40:41], v[40:41], v[82:83] op_sel_hi:[1,0]
	v_pk_mul_f32 v[38:39], v[38:39], v[82:83] op_sel_hi:[1,0]
	v_pk_mul_f32 v[36:37], v[36:37], v[82:83] op_sel_hi:[1,0]
	v_pk_mul_f32 v[34:35], v[34:35], v[82:83] op_sel_hi:[1,0]
	v_pk_mul_f32 v[32:33], v[32:33], v[82:83] op_sel_hi:[1,0]
	v_pk_mul_f32 v[30:31], v[30:31], v[82:83] op_sel_hi:[1,0]
	v_pk_mul_f32 v[28:29], v[28:29], v[82:83] op_sel_hi:[1,0]
	v_pk_mul_f32 v[26:27], v[26:27], v[82:83] op_sel_hi:[1,0]
	v_pk_mul_f32 v[24:25], v[24:25], v[82:83] op_sel_hi:[1,0]
	v_pk_mul_f32 v[22:23], v[22:23], v[82:83] op_sel_hi:[1,0]
	v_pk_mul_f32 v[20:21], v[20:21], v[82:83] op_sel_hi:[1,0]
	v_pk_mul_f32 v[18:19], v[18:19], v[82:83] op_sel_hi:[1,0]
	v_pk_mul_f32 v[16:17], v[16:17], v[82:83] op_sel_hi:[1,0]
	v_pk_mul_f32 v[14:15], v[14:15], v[82:83] op_sel_hi:[1,0]
	v_pk_mul_f32 v[12:13], v[12:13], v[82:83] op_sel_hi:[1,0]
	v_pk_mul_f32 v[10:11], v[10:11], v[82:83] op_sel_hi:[1,0]
	v_pk_mul_f32 v[8:9], v[8:9], v[82:83] op_sel_hi:[1,0]
	v_pk_mul_f32 v[6:7], v[6:7], v[82:83] op_sel_hi:[1,0]
	v_pk_mul_f32 v[4:5], v[4:5], v[82:83] op_sel_hi:[1,0]
	v_pk_mul_f32 v[2:3], v[2:3], v[82:83] op_sel_hi:[1,0]
	v_pk_mul_f32 v[0:1], v[0:1], v[82:83] op_sel_hi:[1,0]

.LBB0_867:
	v_exp_f32_e32 v113, v80
	v_exp_f32_e32 v122, v81
	v_mfma_f32_32x32x16_bf16 v[96:111], v[252:255], v[144:147], v[64:79]
	ds_read_b128 v[248:251], v220 offset:32768
	v_exp_f32_e32 v123, v82
	v_exp_f32_e32 v124, v83
	v_mfma_f32_32x32x16_bf16 v[96:111], v[176:179], v[156:159], v[96:111]
	ds_read_b128 v[252:255], v221 offset:32768
	v_exp_f32_e32 v125, v84
	v_exp_f32_e32 v126, v85
	v_mfma_f32_32x32x16_bf16 v[96:111], v[180:183], v[168:171], v[96:111]
	ds_read_b128 v[176:179], v206 offset:16384
	v_exp_f32_e32 v127, v86
	v_exp_f32_e32 v230, v87
	v_mfma_f32_32x32x16_bf16 v[96:111], v[236:239], v[172:175], v[96:111]
	ds_read_b128 v[180:183], v208 offset:16384
	v_exp_f32_e32 v88, v88
	v_exp_f32_e32 v89, v89
	v_mfma_f32_32x32x16_bf16 v[96:111], v[240:243], v[164:167], v[96:111]
	ds_read_b128 v[236:239], v210 offset:16384
	v_exp_f32_e32 v90, v90
	v_exp_f32_e32 v91, v91
	s_waitcnt lgkmcnt(4)
	v_mfma_f32_32x32x16_bf16 v[96:111], v[244:247], v[160:163], v[96:111]
	ds_read_b128 v[240:243], v212 offset:16384
	v_exp_f32_e32 v92, v92
	v_exp_f32_e32 v93, v93
	v_mfma_f32_32x32x16_bf16 v[96:111], v[248:251], v[152:155], v[96:111]
	ds_read_b128 v[244:247], v227 offset:16384
	v_exp_f32_e32 v94, v94
	v_exp_f32_e32 v95, v95
	s_waitcnt lgkmcnt(4)
	v_mfma_f32_32x32x16_bf16 v[96:111], v[252:255], v[148:151], v[96:111]
	ds_read_b128 v[248:251], v227 offset:20480
	v_mfma_f32_32x32x16_bf16 v[96:111], v[176:179], v[140:143], v[96:111]
	ds_read_b128 v[252:255], v227 offset:24576
	s_waitcnt lgkmcnt(4)
	v_mfma_f32_32x32x16_bf16 v[96:111], v[180:183], v[136:139], v[96:111]
	ds_read_b128 v[176:179], v227 offset:28672
	v_mfma_f32_32x32x16_bf16 v[96:111], v[236:239], v[132:135], v[96:111]
	ds_read_b128 v[180:183], v228 offset:20480
	v_cvt_pk_bf16_f32 v114, v113, v122
	v_cvt_pk_bf16_f32 v115, v123, v124
	v_cvt_pk_bf16_f32 v116, v125, v126
	v_cvt_pk_bf16_f32 v117, v127, v230
	s_waitcnt lgkmcnt(4)
	v_mfma_f32_32x32x16_bf16 v[96:111], v[240:243], v[128:131], v[96:111]
	ds_read_b128 v[236:239], v228 offset:16384
	v_add_f32_e32 v118, 0, v113
	v_add_f32_e32 v113, v122, v118
	v_add_f32_e32 v113, v123, v113
	v_mfma_f32_32x32x16_bf16 v[48:63], v[244:247], v[114:117], v[48:63]
	ds_read_b128 v[240:243], v228 offset:24576
	v_add_f32_e32 v80, v124, v113
	v_add_f32_e32 v80, v125, v80
	v_add_f32_e32 v80, v126, v80
	v_add_f32_e32 v113, v127, v80
	s_waitcnt lgkmcnt(4)
	v_mfma_f32_32x32x16_bf16 v[32:47], v[248:251], v[114:117], v[32:47]
	ds_read_b128 v[244:247], v228 offset:28672
	v_add_f32_e32 v84, v230, v113
	v_add_f32_e32 v84, v88, v84
	v_add_f32_e32 v113, v89, v84
	v_mfma_f32_32x32x16_bf16 v[16:31], v[252:255], v[114:117], v[16:31]
	ds_read_b128 v[248:251], v214 offset:40960
	v_add_f32_e32 v80, v90, v113
	v_add_f32_e32 v80, v91, v80
	v_add_f32_e32 v80, v92, v80
	v_add_f32_e32 v113, v93, v80
	v_add_f32_e32 v113, v94, v113
	s_waitcnt lgkmcnt(4)
	v_mfma_f32_32x32x16_bf16 v[0:15], v[176:179], v[114:117], v[0:15]
	ds_read_b128 v[252:255], v215 offset:40960
	v_cvt_pk_bf16_f32 v84, v88, v89
	v_cvt_pk_bf16_f32 v85, v90, v91
	v_cvt_pk_bf16_f32 v86, v92, v93
	v_max_f32_e32 v92, v97, v97
	v_max_f32_e32 v93, v96, v96
	v_max_f32_e32 v92, v93, v92
	v_max3_f32 v92, v92, v98, v99
	v_max3_f32 v92, v92, v100, v101
	v_cvt_pk_bf16_f32 v87, v94, v95
	v_max3_f32 v92, v92, v102, v103
	v_add_f32_e32 v94, v95, v113
	v_mfma_f32_32x32x16_bf16 v[32:47], v[180:183], v[84:87], v[32:47]
	ds_read_b128 v[176:179], v216 offset:40960
	v_max3_f32 v88, v92, v104, v105
	v_max3_f32 v88, v88, v106, v107
	v_max3_f32 v88, v88, v108, v109
	v_max3_f32 v92, v88, v110, v111
	ds_bpermute_b32 v93, v229, v92
	v_add_f32_e32 v112, v112, v94
	s_waitcnt lgkmcnt(5)
	v_mfma_f32_32x32x16_bf16 v[48:63], v[236:239], v[84:87], v[48:63]
	ds_read_b128 v[180:183], v217 offset:40960
	s_waitcnt vmcnt(0)
	s_barrier
	v_mfma_f32_32x32x16_bf16 v[16:31], v[240:243], v[84:87], v[16:31]
	ds_read_b128 v[236:239], v218 offset:40960
	s_waitcnt lgkmcnt(2)
	v_max_f32_e32 v80, v93, v93
	v_max_f32_e32 v80, v92, v80
	v_cmp_lt_f32_e32 vcc, 0, v80
	v_mfma_f32_32x32x16_bf16 v[0:15], v[244:247], v[84:87], v[0:15]
	ds_read_b128 v[240:243], v219 offset:40960
	s_cbranch_vccz .LBB0_869
	v_max_f32_e32 v80, v80, v80
	v_max_f32_e32 v80, 0, v80
	v_exp_f32_e64 v82, -v80
	v_pk_add_f32 v[96:97], v[96:97], v[80:81] op_sel_hi:[1,0] neg_lo:[0,1] neg_hi:[0,1]
	v_pk_add_f32 v[98:99], v[98:99], v[80:81] op_sel_hi:[1,0] neg_lo:[0,1] neg_hi:[0,1]
	v_pk_add_f32 v[100:101], v[100:101], v[80:81] op_sel_hi:[1,0] neg_lo:[0,1] neg_hi:[0,1]
	v_mul_f32_e32 v112, v112, v82
	v_pk_add_f32 v[102:103], v[102:103], v[80:81] op_sel_hi:[1,0] neg_lo:[0,1] neg_hi:[0,1]
	v_pk_add_f32 v[104:105], v[104:105], v[80:81] op_sel_hi:[1,0] neg_lo:[0,1] neg_hi:[0,1]
	v_pk_add_f32 v[106:107], v[106:107], v[80:81] op_sel_hi:[1,0] neg_lo:[0,1] neg_hi:[0,1]
	v_pk_add_f32 v[108:109], v[108:109], v[80:81] op_sel_hi:[1,0] neg_lo:[0,1] neg_hi:[0,1]
	v_sub_f32_e32 v79, v79, v80
	v_sub_f32_e32 v78, v78, v80
	v_sub_f32_e32 v77, v77, v80
	v_sub_f32_e32 v76, v76, v80
	v_sub_f32_e32 v75, v75, v80
	v_sub_f32_e32 v74, v74, v80
	v_sub_f32_e32 v73, v73, v80
	v_sub_f32_e32 v72, v72, v80
	v_sub_f32_e32 v71, v71, v80
	v_sub_f32_e32 v70, v70, v80
	v_sub_f32_e32 v69, v69, v80
	v_sub_f32_e32 v68, v68, v80
	v_sub_f32_e32 v67, v67, v80
	v_sub_f32_e32 v66, v66, v80
	v_sub_f32_e32 v65, v65, v80
	v_sub_f32_e32 v64, v64, v80
	v_pk_add_f32 v[110:111], v[110:111], v[80:81] op_sel_hi:[1,0] neg_lo:[0,1] neg_hi:[0,1]
	v_pk_mul_f32 v[62:63], v[62:63], v[82:83] op_sel_hi:[1,0]
	v_pk_mul_f32 v[60:61], v[60:61], v[82:83] op_sel_hi:[1,0]
	v_pk_mul_f32 v[58:59], v[58:59], v[82:83] op_sel_hi:[1,0]
	v_pk_mul_f32 v[56:57], v[56:57], v[82:83] op_sel_hi:[1,0]
	v_pk_mul_f32 v[54:55], v[54:55], v[82:83] op_sel_hi:[1,0]
	v_pk_mul_f32 v[52:53], v[52:53], v[82:83] op_sel_hi:[1,0]
	v_pk_mul_f32 v[50:51], v[50:51], v[82:83] op_sel_hi:[1,0]
	v_pk_mul_f32 v[48:49], v[48:49], v[82:83] op_sel_hi:[1,0]
	v_pk_mul_f32 v[46:47], v[46:47], v[82:83] op_sel_hi:[1,0]
	v_pk_mul_f32 v[44:45], v[44:45], v[82:83] op_sel_hi:[1,0]
	v_pk_mul_f32 v[42:43], v[42:43], v[82:83] op_sel_hi:[1,0]
	v_pk_mul_f32 v[40:41], v[40:41], v[82:83] op_sel_hi:[1,0]
	v_pk_mul_f32 v[38:39], v[38:39], v[82:83] op_sel_hi:[1,0]
	v_pk_mul_f32 v[36:37], v[36:37], v[82:83] op_sel_hi:[1,0]
	v_pk_mul_f32 v[34:35], v[34:35], v[82:83] op_sel_hi:[1,0]
	v_pk_mul_f32 v[32:33], v[32:33], v[82:83] op_sel_hi:[1,0]
	v_pk_mul_f32 v[30:31], v[30:31], v[82:83] op_sel_hi:[1,0]
	v_pk_mul_f32 v[28:29], v[28:29], v[82:83] op_sel_hi:[1,0]
	v_pk_mul_f32 v[26:27], v[26:27], v[82:83] op_sel_hi:[1,0]
	v_pk_mul_f32 v[24:25], v[24:25], v[82:83] op_sel_hi:[1,0]
	v_pk_mul_f32 v[22:23], v[22:23], v[82:83] op_sel_hi:[1,0]
	v_pk_mul_f32 v[20:21], v[20:21], v[82:83] op_sel_hi:[1,0]
	v_pk_mul_f32 v[18:19], v[18:19], v[82:83] op_sel_hi:[1,0]
	v_pk_mul_f32 v[16:17], v[16:17], v[82:83] op_sel_hi:[1,0]
	v_pk_mul_f32 v[14:15], v[14:15], v[82:83] op_sel_hi:[1,0]
	v_pk_mul_f32 v[12:13], v[12:13], v[82:83] op_sel_hi:[1,0]
	v_pk_mul_f32 v[10:11], v[10:11], v[82:83] op_sel_hi:[1,0]
	v_pk_mul_f32 v[8:9], v[8:9], v[82:83] op_sel_hi:[1,0]
	v_pk_mul_f32 v[6:7], v[6:7], v[82:83] op_sel_hi:[1,0]
	v_pk_mul_f32 v[4:5], v[4:5], v[82:83] op_sel_hi:[1,0]
	v_pk_mul_f32 v[2:3], v[2:3], v[82:83] op_sel_hi:[1,0]
	v_pk_mul_f32 v[0:1], v[0:1], v[82:83] op_sel_hi:[1,0]

.LBB0_873:
	v_exp_f32_e32 v113, v80
	v_exp_f32_e32 v126, v85
	v_mfma_f32_32x32x16_bf16 v[96:111], v[244:247], v[144:147], v[64:79]
	ds_read_b128 v[240:243], v220
	v_exp_f32_e32 v127, v86
	v_exp_f32_e32 v230, v87
	v_add_f32_e32 v231, 0, v113
	v_mfma_f32_32x32x16_bf16 v[96:111], v[248:251], v[156:159], v[96:111]
	ds_read_b128 v[244:247], v221
	v_exp_f32_e32 v88, v88
	v_exp_f32_e32 v89, v89
	s_add_u32 s62, s62, 0x180
	s_addc_u32 s61, s61, 0
	s_add_u32 s60, s60, 0x12000
	s_addc_u32 s59, s59, 0
	s_add_i32 s4, s16, 3
	v_mfma_f32_32x32x16_bf16 v[96:111], v[252:255], v[168:171], v[96:111]
	ds_read_b128 v[248:251], v206
	v_exp_f32_e32 v90, v90
	v_exp_f32_e32 v91, v91
	s_cmp_le_u32 s4, s9
	v_mfma_f32_32x32x16_bf16 v[96:111], v[176:179], v[172:175], v[96:111]
	ds_read_b128 v[252:255], v208
	v_exp_f32_e32 v92, v92
	v_exp_f32_e32 v93, v93
	v_mfma_f32_32x32x16_bf16 v[96:111], v[180:183], v[164:167], v[96:111]
	ds_read_b128 v[176:179], v210
	v_exp_f32_e32 v118, v81
	v_exp_f32_e32 v119, v82
	s_waitcnt lgkmcnt(4)
	v_mfma_f32_32x32x16_bf16 v[96:111], v[236:239], v[160:163], v[96:111]
	ds_read_b128 v[180:183], v212
	v_exp_f32_e32 v120, v83
	v_exp_f32_e32 v121, v84
	v_mfma_f32_32x32x16_bf16 v[96:111], v[240:243], v[152:155], v[96:111]
	ds_read_b128 v[236:239], v227 offset:32768
	s_waitcnt lgkmcnt(4)
	v_mfma_f32_32x32x16_bf16 v[96:111], v[244:247], v[148:151], v[96:111]
	ds_read_b128 v[240:243], v227 offset:36864
	v_mfma_f32_32x32x16_bf16 v[96:111], v[248:251], v[140:143], v[96:111]
	ds_read_b128 v[244:247], v227 offset:40960
	s_waitcnt lgkmcnt(4)
	v_mfma_f32_32x32x16_bf16 v[96:111], v[252:255], v[136:139], v[96:111]
	ds_read_b128 v[248:251], v227 offset:45056
	v_mfma_f32_32x32x16_bf16 v[96:111], v[176:179], v[132:135], v[96:111]
	ds_read_b128 v[252:255], v228 offset:36864
	v_cvt_pk_bf16_f32 v114, v113, v118
	v_add_f32_e32 v113, v118, v231
	v_add_f32_e32 v113, v119, v113
	v_add_f32_e32 v113, v120, v113
	v_add_f32_e32 v113, v121, v113
	v_cvt_pk_bf16_f32 v115, v119, v120
	v_cvt_pk_bf16_f32 v116, v121, v126
	v_cvt_pk_bf16_f32 v117, v127, v230
	v_add_f32_e32 v113, v126, v113
	s_waitcnt lgkmcnt(4)
	v_mfma_f32_32x32x16_bf16 v[96:111], v[180:183], v[128:131], v[96:111]
	ds_read_b128 v[176:179], v228 offset:32768
	v_exp_f32_e32 v118, v94
	v_exp_f32_e32 v119, v95
	v_mfma_f32_32x32x16_bf16 v[48:63], v[236:239], v[114:117], v[48:63]
	ds_read_b128 v[180:183], v228 offset:40960
	v_add_f32_e32 v80, v127, v113
	v_add_f32_e32 v80, v230, v80
	v_add_f32_e32 v113, v88, v80
	v_cvt_pk_bf16_f32 v88, v88, v89
	s_waitcnt lgkmcnt(4)
	v_mfma_f32_32x32x16_bf16 v[32:47], v[240:243], v[114:117], v[32:47]
	ds_read_b128 v[236:239], v228 offset:45056
	v_add_f32_e32 v84, v89, v113
	v_add_f32_e32 v84, v90, v84
	v_add_f32_e32 v84, v91, v84
	v_add_f32_e32 v113, v92, v84
	v_add_f32_e32 v113, v93, v113
	v_cvt_pk_bf16_f32 v89, v90, v91
	v_mfma_f32_32x32x16_bf16 v[16:31], v[244:247], v[114:117], v[16:31]
	v_cvt_pk_bf16_f32 v90, v92, v93
	v_cvt_pk_bf16_f32 v91, v118, v119
	s_waitcnt lgkmcnt(3)
	v_mfma_f32_32x32x16_bf16 v[0:15], v[248:251], v[114:117], v[0:15]
	v_max_f32_e32 v114, v97, v97
	v_max_f32_e32 v115, v96, v96
	v_max_f32_e32 v114, v115, v114
	v_max3_f32 v114, v114, v98, v99
	v_mfma_f32_32x32x16_bf16 v[32:47], v[252:255], v[88:91], v[32:47]
	s_waitcnt vmcnt(0)
	s_barrier
	s_waitcnt lgkmcnt(2)
	v_mfma_f32_32x32x16_bf16 v[48:63], v[176:179], v[88:91], v[48:63]
	v_max3_f32 v80, v114, v100, v101
	v_max3_f32 v80, v80, v102, v103
	v_max3_f32 v80, v80, v104, v105
	v_max3_f32 v80, v80, v106, v107
	v_max3_f32 v80, v80, v108, v109
	v_max3_f32 v80, v80, v110, v111
	ds_bpermute_b32 v81, v229, v80
	s_waitcnt lgkmcnt(2)
	v_mfma_f32_32x32x16_bf16 v[16:31], v[180:183], v[88:91], v[16:31]
	v_add_f32_e32 v82, v118, v113
	v_add_f32_e32 v82, v119, v82
	v_add_f32_e32 v230, v112, v82
	s_waitcnt lgkmcnt(0)
	v_max_f32_e32 v81, v81, v81
	v_max_f32_e32 v82, v80, v81
	v_mfma_f32_32x32x16_bf16 v[0:15], v[236:239], v[88:91], v[0:15]
	s_cbranch_scc0 .LBB0_875
	s_mov_b32 s8, s16
	v_cmp_lt_f32_e32 vcc, 0, v82
	s_cbranch_vccnz .LBB0_858
	s_branch .LBB0_859
